# idle-slot weight conversion: counted vmcnt ladder before the LDS writes instead of one vmcnt(0)
# baseline (speedup 1.0000x reference)
; __device__ __forceinline__ void conv_item(const float* __restrict__ W, int N, bf16_t* __restrict__ WT, int ldk, int mode, int row_off, int n_lo, int nblk, ...
;     const int kb = item / nblk, nb = item % nblk, k0 = 64 * kb, n0 = n_lo + 32 * nb;
;     const float s = sc * (sn ? sn[n0 + (lane & 31)] : 1.f);
;     const float* wp = W + (size_t)(k0 + (lane >> 5)) * N + n0 + (lane & 31);
;     float v[32];
; #pragma unroll
;     for (int i = 0; i < 32; ++i) v[i] = __builtin_nontemporal_load(wp + (size_t)(2 * i) * N);
; #pragma unroll
;     for (int i = 0; i < 32; ++i) scr[(2 * i + (lane >> 5)) * 33 + (lane & 31)] = v[i] * s;
.LBB0_704:
	s_ashr_i32 s14, s24, 31
	s_lshr_b32 s14, s14, 26
	s_add_i32 s14, s24, s14
	s_ashr_i32 s28, s14, 6
	s_andn2_b32 s14, s14, 63
	v_or_b32_e32 v6, s14, v1
	s_lshl_b32 s15, s28, 11
	v_ashrrev_i32_e32 v7, 31, v6
	s_sub_i32 s30, s25, s15
	v_lshlrev_b64 v[6:7], 13, v[6:7]
	v_lshl_add_u64 v[6:7], s[12:13], 0, v[6:7]
	s_ashr_i32 s31, s30, 31
	v_lshl_add_u64 v[6:7], s[30:31], 2, v[6:7]
	v_lshl_add_u64 v[6:7], v[6:7], 0, v[176:177]
	v_add_co_u32_e32 v18, vcc, s94, v6
	global_load_dword v11, v[6:7], off nt
	s_nop 0
	v_addc_co_u32_e32 v19, vcc, 0, v7, vcc
	global_load_dword v17, v[18:19], off nt
	v_add_co_u32_e32 v18, vcc, s36, v6
	s_mul_i32 s28, s28, 0xff500000
	s_nop 0
	v_addc_co_u32_e32 v19, vcc, 0, v7, vcc
	global_load_dword v20, v[18:19], off nt
	v_add_co_u32_e32 v18, vcc, s97, v6
	s_ashr_i32 s15, s14, 31
	s_nop 0
	v_addc_co_u32_e32 v19, vcc, 0, v7, vcc
	global_load_dword v21, v[18:19], off nt
	v_add_co_u32_e32 v18, vcc, s96, v6
	s_add_i32 s24, s24, s88
	s_nop 0
	v_addc_co_u32_e32 v19, vcc, 0, v7, vcc
	global_load_dword v22, v[18:19], off nt
	v_add_co_u32_e32 v18, vcc, s69, v6
	s_add_i32 s25, s25, s27
	s_nop 0
	v_addc_co_u32_e32 v19, vcc, 0, v7, vcc
	global_load_dword v23, v[18:19], off nt
	v_add_co_u32_e32 v18, vcc, s37, v6
	s_cmpk_lt_i32 s24, 0x1600
	s_nop 0
	v_addc_co_u32_e32 v19, vcc, 0, v7, vcc
	global_load_dword v24, v[18:19], off nt
	v_add_co_u32_e32 v18, vcc, s39, v6
	s_nop 1
	v_addc_co_u32_e32 v19, vcc, 0, v7, vcc
	global_load_dword v25, v[18:19], off nt
	v_add_co_u32_e32 v18, vcc, s38, v6
	s_nop 1
	v_addc_co_u32_e32 v19, vcc, 0, v7, vcc
	global_load_dword v26, v[18:19], off nt
	v_add_co_u32_e32 v18, vcc, s52, v6
	s_nop 1
	v_addc_co_u32_e32 v19, vcc, 0, v7, vcc
	global_load_dword v27, v[18:19], off nt
	v_add_co_u32_e32 v18, vcc, s53, v6
	s_nop 1
	v_addc_co_u32_e32 v19, vcc, 0, v7, vcc
	global_load_dword v28, v[18:19], off nt
	v_add_co_u32_e32 v18, vcc, s29, v6
	s_nop 1
	v_addc_co_u32_e32 v19, vcc, 0, v7, vcc
	global_load_dword v29, v[18:19], off nt
	v_add_co_u32_e32 v18, vcc, s35, v6
	s_nop 1
	v_addc_co_u32_e32 v19, vcc, 0, v7, vcc
	global_load_dword v30, v[18:19], off nt
	v_add_co_u32_e32 v18, vcc, s58, v6
	s_nop 1
	v_addc_co_u32_e32 v19, vcc, 0, v7, vcc
	global_load_dword v31, v[18:19], off nt
	v_add_co_u32_e32 v18, vcc, s59, v6
	s_nop 1
	v_addc_co_u32_e32 v19, vcc, 0, v7, vcc
	global_load_dword v32, v[18:19], off nt
	v_add_co_u32_e32 v18, vcc, s60, v6
	s_nop 1
	v_addc_co_u32_e32 v19, vcc, 0, v7, vcc
	global_load_dword v33, v[18:19], off nt
	v_add_co_u32_e32 v18, vcc, s34, v6
	s_nop 1
	v_addc_co_u32_e32 v19, vcc, 0, v7, vcc
	global_load_dword v34, v[18:19], off nt
	v_add_co_u32_e32 v18, vcc, s61, v6
	s_nop 1
	v_addc_co_u32_e32 v19, vcc, 0, v7, vcc
	global_load_dword v35, v[18:19], off nt
	v_add_co_u32_e32 v18, vcc, s62, v6
	s_nop 1
	v_addc_co_u32_e32 v19, vcc, 0, v7, vcc
	global_load_dword v36, v[18:19], off nt
	v_add_co_u32_e32 v18, vcc, s63, v6
	s_nop 1
	v_addc_co_u32_e32 v19, vcc, 0, v7, vcc
	global_load_dword v37, v[18:19], off nt
	v_add_co_u32_e32 v18, vcc, s41, v6
	s_nop 1
	v_addc_co_u32_e32 v19, vcc, 0, v7, vcc
	global_load_dword v38, v[18:19], off nt
	v_add_co_u32_e32 v18, vcc, s42, v6
	s_nop 1
	v_addc_co_u32_e32 v19, vcc, 0, v7, vcc
	global_load_dword v39, v[18:19], off nt
	v_add_co_u32_e32 v18, vcc, s43, v6
	s_nop 1
	v_addc_co_u32_e32 v19, vcc, 0, v7, vcc
	global_load_dword v40, v[18:19], off nt
	v_add_co_u32_e32 v18, vcc, s44, v6
	s_nop 1
	v_addc_co_u32_e32 v19, vcc, 0, v7, vcc
	global_load_dword v41, v[18:19], off nt
	v_add_co_u32_e32 v18, vcc, s49, v6
	s_nop 1
	v_addc_co_u32_e32 v19, vcc, 0, v7, vcc
	global_load_dword v42, v[18:19], off nt
	v_add_co_u32_e32 v18, vcc, s45, v6
	s_nop 1
	v_addc_co_u32_e32 v19, vcc, 0, v7, vcc
	global_load_dword v43, v[18:19], off nt
	v_add_co_u32_e32 v18, vcc, s46, v6
	s_nop 1
	v_addc_co_u32_e32 v19, vcc, 0, v7, vcc
	global_load_dword v44, v[18:19], off nt
	v_add_co_u32_e32 v18, vcc, s47, v6
	s_nop 1
	v_addc_co_u32_e32 v19, vcc, 0, v7, vcc
	global_load_dword v45, v[18:19], off nt
	v_add_co_u32_e32 v18, vcc, s48, v6
	s_nop 1
	v_addc_co_u32_e32 v19, vcc, 0, v7, vcc
	global_load_dword v46, v[18:19], off nt
	v_add_co_u32_e32 v18, vcc, s50, v6
	s_nop 1
	v_addc_co_u32_e32 v19, vcc, 0, v7, vcc
	global_load_dword v47, v[18:19], off nt
	v_add_co_u32_e32 v18, vcc, s64, v6
	s_nop 1
	v_addc_co_u32_e32 v19, vcc, 0, v7, vcc
	v_add_co_u32_e32 v6, vcc, s65, v6
	global_load_dword v18, v[18:19], off nt
	s_nop 0
	v_addc_co_u32_e32 v7, vcc, 0, v7, vcc
	global_load_dword v6, v[6:7], off nt
	v_add_u32_e32 v7, 0x400, v10
	s_waitcnt vmcnt(30)
; #define LAS __attribute__((address_space(3)))
; __device__ __forceinline__ unsigned cvt_pk_bf16(float lo, float hi) { unsigned r; asm("v_cvt_pk_bf16_f32 %0, %1, %2" : "=v"(r) : "v"(lo), "v"(hi)); return r; }
; __device__ __forceinline__ unsigned cvt_pk_f16(float lo, float hi) { if (X_BF16) return cvt_pk_bf16(lo, hi); const h16x2 v = {(_Float16)lo, (_Float16)hi}; return __builtin_bit_cast(unsigned, v); }
; __device__ __forceinline__ void conv_item(const float* __restrict__ W, int N, bf16_t* __restrict__ WT, int ldk, int mode, int row_off, int n_lo, int nblk, ...
;     ...
;     for (int i = 0; i < 32; ++i) scr[(2 * i + (lane >> 5)) * 33 + (lane & 31)] = v[i] * s;
;     asm volatile("s_waitcnt lgkmcnt(0)" ::: "memory");
;     const int c = lane & 7;
;     f32x4 g0 = {1.f, 1.f, 1.f, 1.f}, g1 = g0;
;     if (gk) { g0 = *(const f32x4*)(gk + k0 + 8 * c); g1 = *(const f32x4*)(gk + k0 + 8 * c + 4); }
;     const int nn0 = n0 - n_lo;
;     const int drow0 = (mode == 0) ? row_off + nn0 : 256 * (nn0 >> 7) + 128 * (mode - 1) + (nn0 & 127);
; #pragma unroll
;     for (int j = 0; j < 4; ++j) { const int n = (lane >> 3) + 8 * j; const LAS float* sp = scr + (8 * c) * 33 + n;
;         const float e0 = sp[0 * 33] * g0[0], e1 = sp[1 * 33] * g0[1], e2 = sp[2 * 33] * g0[2], e3 = sp[3 * 33] * g0[3], e4 = sp[4 * 33] * g1[0], e5 = sp[5 * 33] * g1[1], e6 = sp[6 * 33] * g1[2], e7 = sp[7 * 33] * g1[3];
;         u32x4 o;
;         if (f16) { o.x = pg8::cvt_pk_f16(e0, e1); o.y = pg8::cvt_pk_f16(e2, e3); o.z = pg8::cvt_pk_f16(e4, e5); o.w = pg8::cvt_pk_f16(e6, e7); }
;         else { o.x = cvt_pk_bf16(e0, e1); o.y = cvt_pk_bf16(e2, e3); o.z = cvt_pk_bf16(e4, e5); o.w = cvt_pk_bf16(e6, e7); }
;         *(u32x4*)(WT + (size_t)(drow0 + n) * ldk + k0 + 8 * c) = o; }
	ds_write2_b32 v10, v11, v17 offset1:66
	s_waitcnt vmcnt(28)
	ds_write2_b32 v10, v20, v21 offset0:132 offset1:198
	s_waitcnt vmcnt(26)
	ds_write2_b32 v7, v22, v23 offset0:8 offset1:74
	s_waitcnt vmcnt(24)
	ds_write2_b32 v7, v24, v25 offset0:140 offset1:206
	v_add_u32_e32 v7, 0x800, v10
	s_waitcnt vmcnt(22)
	ds_write2_b32 v7, v26, v27 offset0:16 offset1:82
	s_waitcnt vmcnt(20)
	ds_write2_b32 v7, v28, v29 offset0:148 offset1:214
	v_add_u32_e32 v7, 0xc00, v10
	s_waitcnt vmcnt(18)
	ds_write2_b32 v7, v30, v31 offset0:24 offset1:90
	s_waitcnt vmcnt(16)
	ds_write2_b32 v7, v32, v33 offset0:156 offset1:222
	v_add_u32_e32 v7, 0x1000, v10
	s_waitcnt vmcnt(14)
	ds_write2_b32 v7, v34, v35 offset0:32 offset1:98
	s_waitcnt vmcnt(12)
	ds_write2_b32 v7, v36, v37 offset0:164 offset1:230
	v_add_u32_e32 v7, 0x1400, v10
	s_waitcnt vmcnt(10)
	ds_write2_b32 v7, v38, v39 offset0:40 offset1:106
	s_waitcnt vmcnt(8)
	ds_write2_b32 v7, v40, v41 offset0:172 offset1:238
	v_add_u32_e32 v7, 0x1800, v10
	s_waitcnt vmcnt(6)
	ds_write2_b32 v7, v42, v43 offset0:48 offset1:114
	s_waitcnt vmcnt(4)
	ds_write2_b32 v7, v44, v45 offset0:180 offset1:246
	v_add_u32_e32 v7, 0x1c00, v10
	s_waitcnt vmcnt(2)
	ds_write2_b32 v7, v46, v47 offset0:56 offset1:122
	s_waitcnt vmcnt(0)
	ds_write2_b32 v7, v18, v6 offset0:188 offset1:254
	s_waitcnt lgkmcnt(0)
	ds_read2_b32 v[22:23], v3 offset0:33 offset1:41
	ds_read2_b32 v[24:25], v3 offset1:8
	ds_read2_b32 v[26:27], v3 offset0:66 offset1:74
	ds_read2_b32 v[28:29], v3 offset0:99 offset1:107
	ds_read2_b32 v[30:31], v3 offset0:132 offset1:140
	ds_read2_b32 v[32:33], v3 offset0:165 offset1:173
	ds_read2_b32 v[34:35], v3 offset0:198 offset1:206
	ds_read2_b32 v[36:37], v3 offset0:231 offset1:239
	v_add_u32_e32 v38, s28, v9
	v_lshl_add_u64 v[6:7], s[14:15], 1, v[4:5]
	v_ashrrev_i32_e32 v39, 31, v38
	s_waitcnt lgkmcnt(6)
	v_cvt_pk_bf16_f32 v18, v24, v22
	v_lshl_add_u64 v[40:41], v[38:39], 1, v[6:7]
	v_add_u32_e32 v22, 0xb000, v38
	s_waitcnt lgkmcnt(4)
	v_cvt_pk_bf16_f32 v19, v26, v28
	s_waitcnt lgkmcnt(2)
	v_cvt_pk_bf16_f32 v20, v30, v32
	s_waitcnt lgkmcnt(0)
	v_cvt_pk_bf16_f32 v21, v34, v36
	global_store_dwordx4 v[40:41], v[18:21], off sc0 sc1
	v_add_u32_e32 v40, 0x16000, v38
	v_ashrrev_i32_e32 v41, 31, v40
	v_cvt_pk_bf16_f32 v18, v25, v23
	v_ashrrev_i32_e32 v23, 31, v22
	v_lshl_add_u64 v[22:23], v[22:23], 1, v[6:7]
	v_cvt_pk_bf16_f32 v19, v27, v29
	v_cvt_pk_bf16_f32 v20, v31, v33
	v_cvt_pk_bf16_f32 v21, v35, v37
	global_store_dwordx4 v[22:23], v[18:21], off sc0 sc1
	ds_read2_b32 v[22:23], v3 offset0:16 offset1:24
	ds_read2_b32 v[24:25], v3 offset0:49 offset1:57
	ds_read2_b32 v[26:27], v3 offset0:82 offset1:90
	ds_read2_b32 v[28:29], v3 offset0:115 offset1:123
	ds_read2_b32 v[30:31], v3 offset0:148 offset1:156
	ds_read2_b32 v[32:33], v3 offset0:181 offset1:189
	ds_read2_b32 v[34:35], v3 offset0:214 offset1:222
	ds_read2_b32 v[36:37], v3 offset0:247 offset1:255
	s_waitcnt lgkmcnt(6)
	v_cvt_pk_bf16_f32 v18, v22, v24
	v_lshl_add_u64 v[40:41], v[40:41], 1, v[6:7]
	v_add_u32_e32 v22, 0x21000, v38
	s_waitcnt lgkmcnt(4)
	v_cvt_pk_bf16_f32 v19, v26, v28
	s_waitcnt lgkmcnt(2)
	v_cvt_pk_bf16_f32 v20, v30, v32
	s_waitcnt lgkmcnt(0)
	v_cvt_pk_bf16_f32 v21, v34, v36
	global_store_dwordx4 v[40:41], v[18:21], off sc0 sc1
	s_mul_i32 s14, s88, 0x2c000
	v_add_u32_e32 v9, s14, v9
	v_cvt_pk_bf16_f32 v18, v23, v25
	v_ashrrev_i32_e32 v23, 31, v22
	v_lshl_add_u64 v[6:7], v[22:23], 1, v[6:7]
	v_cvt_pk_bf16_f32 v19, v27, v29
	v_cvt_pk_bf16_f32 v20, v31, v33
	v_cvt_pk_bf16_f32 v21, v35, v37
	global_store_dwordx4 v[6:7], v[18:21], off sc0 sc1
	s_waitcnt lgkmcnt(0)
	s_cbranch_scc1 .LBB0_704

; __device__ __forceinline__ void conv_item(const float* __restrict__ W, int N, bf16_t* __restrict__ WT, int ldk, int mode, int row_off, int n_lo, int nblk, ...
;     const int kb = item / nblk, nb = item % nblk, k0 = 64 * kb, n0 = n_lo + 32 * nb;
;     const float s = sc * (sn ? sn[n0 + (lane & 31)] : 1.f);
;     const float* wp = W + (size_t)(k0 + (lane >> 5)) * N + n0 + (lane & 31);
;     float v[32];
; #pragma unroll
;     for (int i = 0; i < 32; ++i) v[i] = __builtin_nontemporal_load(wp + (size_t)(2 * i) * N);
; #pragma unroll
;     for (int i = 0; i < 32; ++i) scr[(2 * i + (lane >> 5)) * 33 + (lane & 31)] = v[i] * s;
;     asm volatile("s_waitcnt lgkmcnt(0)" ::: "memory");
.LBB0_707:
	s_ashr_i32 s14, s27, 31
	s_lshr_b32 s14, s14, 26
	s_add_i32 s14, s27, s14
	s_and_b32 s24, s14, 0xffffffc0
	s_lshl_b32 s14, s14, 5
	v_or_b32_e32 v10, s24, v1
	s_and_b32 s14, s14, 0xfffff800
	v_ashrrev_i32_e32 v11, 31, v10
	s_sub_i32 s14, s28, s14
	v_lshlrev_b64 v[10:11], 13, v[10:11]
	v_lshl_add_u64 v[10:11], s[12:13], 0, v[10:11]
	s_ashr_i32 s15, s14, 31
	v_lshl_add_u64 v[10:11], s[14:15], 2, v[10:11]
	v_lshl_add_u64 v[10:11], v[10:11], 0, v[176:177]
	v_add_co_u32_e32 v18, vcc, s94, v10
	global_load_dword v17, v[10:11], off nt
	s_nop 0
	v_addc_co_u32_e32 v19, vcc, 0, v11, vcc
	global_load_dword v20, v[18:19], off nt
	v_add_co_u32_e32 v18, vcc, s36, v10
	s_ashr_i32 s25, s24, 31
	s_nop 0
	v_addc_co_u32_e32 v19, vcc, 0, v11, vcc
	global_load_dword v21, v[18:19], off nt
	v_add_co_u32_e32 v18, vcc, s97, v10
	s_add_i32 s27, s27, s88
	s_nop 0
	v_addc_co_u32_e32 v19, vcc, 0, v11, vcc
	global_load_dword v22, v[18:19], off nt
	v_add_co_u32_e32 v18, vcc, s96, v10
	s_add_i32 s28, s28, s29
	s_nop 0
	v_addc_co_u32_e32 v19, vcc, 0, v11, vcc
	global_load_dword v23, v[18:19], off nt
	v_add_co_u32_e32 v18, vcc, s69, v10
	s_cmpk_lt_i32 s27, 0x800
	s_nop 0
	v_addc_co_u32_e32 v19, vcc, 0, v11, vcc
	global_load_dword v24, v[18:19], off nt
	v_add_co_u32_e32 v18, vcc, s37, v10
	s_nop 1
	v_addc_co_u32_e32 v19, vcc, 0, v11, vcc
	global_load_dword v25, v[18:19], off nt
	v_add_co_u32_e32 v18, vcc, s39, v10
	s_nop 1
	v_addc_co_u32_e32 v19, vcc, 0, v11, vcc
	global_load_dword v26, v[18:19], off nt
	v_add_co_u32_e32 v18, vcc, s38, v10
	s_nop 1
	v_addc_co_u32_e32 v19, vcc, 0, v11, vcc
	global_load_dword v27, v[18:19], off nt
	v_add_co_u32_e32 v18, vcc, s52, v10
	s_nop 1
	v_addc_co_u32_e32 v19, vcc, 0, v11, vcc
	global_load_dword v28, v[18:19], off nt
	v_add_co_u32_e32 v18, vcc, s53, v10
	s_nop 1
	v_addc_co_u32_e32 v19, vcc, 0, v11, vcc
	global_load_dword v29, v[18:19], off nt
	v_add_co_u32_e32 v18, vcc, s30, v10
	s_nop 1
	v_addc_co_u32_e32 v19, vcc, 0, v11, vcc
	global_load_dword v30, v[18:19], off nt
	v_add_co_u32_e32 v18, vcc, s35, v10
	s_nop 1
	v_addc_co_u32_e32 v19, vcc, 0, v11, vcc
	global_load_dword v31, v[18:19], off nt
	v_add_co_u32_e32 v18, vcc, s58, v10
	s_nop 1
	v_addc_co_u32_e32 v19, vcc, 0, v11, vcc
	global_load_dword v32, v[18:19], off nt
	v_add_co_u32_e32 v18, vcc, s59, v10
	s_nop 1
	v_addc_co_u32_e32 v19, vcc, 0, v11, vcc
	global_load_dword v33, v[18:19], off nt
	v_add_co_u32_e32 v18, vcc, s60, v10
	s_nop 1
	v_addc_co_u32_e32 v19, vcc, 0, v11, vcc
	global_load_dword v34, v[18:19], off nt
	v_add_co_u32_e32 v18, vcc, s34, v10
	s_nop 1
	v_addc_co_u32_e32 v19, vcc, 0, v11, vcc
	global_load_dword v35, v[18:19], off nt
	v_add_co_u32_e32 v18, vcc, s61, v10
	s_nop 1
	v_addc_co_u32_e32 v19, vcc, 0, v11, vcc
	global_load_dword v36, v[18:19], off nt
	v_add_co_u32_e32 v18, vcc, s62, v10
	s_nop 1
	v_addc_co_u32_e32 v19, vcc, 0, v11, vcc
	global_load_dword v37, v[18:19], off nt
	v_add_co_u32_e32 v18, vcc, s63, v10
	s_nop 1
	v_addc_co_u32_e32 v19, vcc, 0, v11, vcc
	global_load_dword v38, v[18:19], off nt
	v_add_co_u32_e32 v18, vcc, s31, v10
	s_nop 1
	v_addc_co_u32_e32 v19, vcc, 0, v11, vcc
	global_load_dword v39, v[18:19], off nt
	v_add_co_u32_e32 v18, vcc, s41, v10
	s_nop 1
	v_addc_co_u32_e32 v19, vcc, 0, v11, vcc
	global_load_dword v40, v[18:19], off nt
	v_add_co_u32_e32 v18, vcc, s42, v10
	s_nop 1
	v_addc_co_u32_e32 v19, vcc, 0, v11, vcc
	global_load_dword v41, v[18:19], off nt
	v_add_co_u32_e32 v18, vcc, s43, v10
	s_nop 1
	v_addc_co_u32_e32 v19, vcc, 0, v11, vcc
	global_load_dword v42, v[18:19], off nt
	v_add_co_u32_e32 v18, vcc, s49, v10
	s_nop 1
	v_addc_co_u32_e32 v19, vcc, 0, v11, vcc
	global_load_dword v43, v[18:19], off nt
	v_add_co_u32_e32 v18, vcc, s44, v10
	s_nop 1
	v_addc_co_u32_e32 v19, vcc, 0, v11, vcc
	global_load_dword v44, v[18:19], off nt
	v_add_co_u32_e32 v18, vcc, s45, v10
	s_nop 1
	v_addc_co_u32_e32 v19, vcc, 0, v11, vcc
	global_load_dword v45, v[18:19], off nt
	v_add_co_u32_e32 v18, vcc, s46, v10
	s_nop 1
	v_addc_co_u32_e32 v19, vcc, 0, v11, vcc
	global_load_dword v46, v[18:19], off nt
	v_add_co_u32_e32 v18, vcc, s47, v10
	s_nop 1
	v_addc_co_u32_e32 v19, vcc, 0, v11, vcc
	global_load_dword v47, v[18:19], off nt
	v_add_co_u32_e32 v18, vcc, s48, v10
	s_nop 1
	v_addc_co_u32_e32 v19, vcc, 0, v11, vcc
	global_load_dword v48, v[18:19], off nt
	v_add_co_u32_e32 v18, vcc, s64, v10
	s_nop 1
	v_addc_co_u32_e32 v19, vcc, 0, v11, vcc
	v_add_co_u32_e32 v10, vcc, s65, v10
	global_load_dword v18, v[18:19], off nt
	s_nop 0
	v_addc_co_u32_e32 v11, vcc, 0, v11, vcc
	global_load_dword v10, v[10:11], off nt
	v_add_u32_e32 v11, 0x400, v5
	s_waitcnt vmcnt(30)
	ds_write2_b32 v5, v17, v20 offset1:66
	s_waitcnt vmcnt(28)
	ds_write2_b32 v5, v21, v22 offset0:132 offset1:198
	s_waitcnt vmcnt(26)
; #define LAS __attribute__((address_space(3)))
; __device__ __forceinline__ unsigned cvt_pk_bf16(float lo, float hi) { unsigned r; asm("v_cvt_pk_bf16_f32 %0, %1, %2" : "=v"(r) : "v"(lo), "v"(hi)); return r; }
; __device__ __forceinline__ unsigned cvt_pk_f16(float lo, float hi) { if (X_BF16) return cvt_pk_bf16(lo, hi); const h16x2 v = {(_Float16)lo, (_Float16)hi}; return __builtin_bit_cast(unsigned, v); }
; __device__ __forceinline__ void conv_item(const float* __restrict__ W, int N, bf16_t* __restrict__ WT, int ldk, int mode, int row_off, int n_lo, int nblk, ...
;     ...
;     for (int i = 0; i < 32; ++i) scr[(2 * i + (lane >> 5)) * 33 + (lane & 31)] = v[i] * s;
;     asm volatile("s_waitcnt lgkmcnt(0)" ::: "memory");
;     const int c = lane & 7;
;     f32x4 g0 = {1.f, 1.f, 1.f, 1.f}, g1 = g0;
;     if (gk) { g0 = *(const f32x4*)(gk + k0 + 8 * c); g1 = *(const f32x4*)(gk + k0 + 8 * c + 4); }
;     const int nn0 = n0 - n_lo;
;     const int drow0 = (mode == 0) ? row_off + nn0 : 256 * (nn0 >> 7) + 128 * (mode - 1) + (nn0 & 127);
; #pragma unroll
;     for (int j = 0; j < 4; ++j) { const int n = (lane >> 3) + 8 * j; const LAS float* sp = scr + (8 * c) * 33 + n;
;         const float e0 = sp[0 * 33] * g0[0], e1 = sp[1 * 33] * g0[1], e2 = sp[2 * 33] * g0[2], e3 = sp[3 * 33] * g0[3], e4 = sp[4 * 33] * g1[0], e5 = sp[5 * 33] * g1[1], e6 = sp[6 * 33] * g1[2], e7 = sp[7 * 33] * g1[3];
;         u32x4 o;
;         if (f16) { o.x = pg8::cvt_pk_f16(e0, e1); o.y = pg8::cvt_pk_f16(e2, e3); o.z = pg8::cvt_pk_f16(e4, e5); o.w = pg8::cvt_pk_f16(e6, e7); }
;         else { o.x = cvt_pk_bf16(e0, e1); o.y = cvt_pk_bf16(e2, e3); o.z = cvt_pk_bf16(e4, e5); o.w = cvt_pk_bf16(e6, e7); }
;         *(u32x4*)(WT + (size_t)(drow0 + n) * ldk + k0 + 8 * c) = o; }
	ds_write2_b32 v11, v23, v24 offset0:8 offset1:74
	s_waitcnt vmcnt(24)
	ds_write2_b32 v11, v25, v26 offset0:140 offset1:206
	v_add_u32_e32 v11, 0x800, v5
	s_waitcnt vmcnt(22)
	ds_write2_b32 v11, v27, v28 offset0:16 offset1:82
	s_waitcnt vmcnt(20)
	ds_write2_b32 v11, v29, v30 offset0:148 offset1:214
	v_add_u32_e32 v11, 0xc00, v5
	s_waitcnt vmcnt(18)
	ds_write2_b32 v11, v31, v32 offset0:24 offset1:90
	s_waitcnt vmcnt(16)
	ds_write2_b32 v11, v33, v34 offset0:156 offset1:222
	v_add_u32_e32 v11, 0x1000, v5
	s_waitcnt vmcnt(14)
	ds_write2_b32 v11, v35, v36 offset0:32 offset1:98
	s_waitcnt vmcnt(12)
	ds_write2_b32 v11, v37, v38 offset0:164 offset1:230
	v_add_u32_e32 v11, 0x1400, v5
	s_waitcnt vmcnt(10)
	ds_write2_b32 v11, v39, v40 offset0:40 offset1:106
	s_waitcnt vmcnt(8)
	ds_write2_b32 v11, v41, v42 offset0:172 offset1:238
	v_add_u32_e32 v11, 0x1800, v5
	s_waitcnt vmcnt(6)
	ds_write2_b32 v11, v43, v44 offset0:48 offset1:114
	s_waitcnt vmcnt(4)
	ds_write2_b32 v11, v45, v46 offset0:180 offset1:246
	v_add_u32_e32 v11, 0x1c00, v5
	s_waitcnt vmcnt(2)
	ds_write2_b32 v11, v47, v48 offset0:56 offset1:122
	s_waitcnt vmcnt(0)
	ds_write2_b32 v11, v18, v10 offset0:188 offset1:254
	s_waitcnt lgkmcnt(0)
	v_lshl_add_u64 v[10:11], s[24:25], 2, v[6:7]
	global_load_dwordx4 v[18:21], v[10:11], off offset:16
	global_load_dwordx4 v[22:25], v[10:11], off
	ds_read2_b32 v[34:35], v3 offset0:66 offset1:74
	ds_read2_b32 v[36:37], v3 offset0:99 offset1:107
	ds_read2_b32 v[30:31], v3 offset1:8
	ds_read2_b32 v[32:33], v3 offset0:33 offset1:41
	ds_read2_b32 v[38:39], v3 offset0:132 offset1:140
	ds_read2_b32 v[40:41], v3 offset0:165 offset1:173
	ds_read2_b32 v[42:43], v3 offset0:198 offset1:206
	ds_read2_b32 v[44:45], v3 offset0:231 offset1:239
	v_add_u32_e32 v46, s14, v12
	v_ashrrev_i32_e32 v47, 31, v46
	v_lshl_add_u64 v[10:11], s[24:25], 1, v[8:9]
	v_lshlrev_b64 v[48:49], 12, v[46:47]
	v_lshl_add_u64 v[48:49], v[10:11], 0, v[48:49]
	s_waitcnt vmcnt(1) lgkmcnt(3)
	v_mul_f32_e32 v29, v18, v38
	s_waitcnt vmcnt(0)
	v_mul_f32_e32 v27, v24, v34
	v_mul_f32_e32 v28, v25, v36
	v_mul_f32_e32 v17, v22, v30
	v_mul_f32_e32 v26, v23, v32
	s_waitcnt lgkmcnt(2)
	v_mul_f32_e32 v30, v19, v40
	v_cvt_pk_bf16_f32 v27, v27, v28
	v_cvt_pk_bf16_f32 v28, v29, v30
	s_waitcnt lgkmcnt(1)
	v_mul_f32_e32 v32, v20, v42
	s_waitcnt lgkmcnt(0)
	v_mul_f32_e32 v34, v21, v44
	v_cvt_pk_bf16_f32 v26, v17, v26
	v_cvt_pk_bf16_f32 v29, v32, v34
	global_store_dwordx4 v[48:49], v[26:29], off sc0 sc1
	v_mul_f32_e32 v30, v19, v41
	v_mul_f32_e32 v17, v22, v31
	v_mul_f32_e32 v27, v24, v35
	v_mul_f32_e32 v28, v25, v37
	v_mul_f32_e32 v29, v18, v39
	v_mul_f32_e32 v31, v20, v43
	v_cvt_pk_bf16_f32 v27, v27, v28
	v_cvt_pk_bf16_f32 v28, v29, v30
	v_add_u32_e32 v30, 8, v46
	v_mul_f32_e32 v32, v21, v45
	v_cvt_pk_bf16_f32 v29, v31, v32
	v_ashrrev_i32_e32 v31, 31, v30
	v_lshlrev_b64 v[30:31], 12, v[30:31]
	v_mul_f32_e32 v26, v23, v33
	v_lshl_add_u64 v[30:31], v[10:11], 0, v[30:31]
	v_cvt_pk_bf16_f32 v26, v17, v26
	global_store_dwordx4 v[30:31], v[26:29], off sc0 sc1
	ds_read2_b32 v[30:31], v3 offset0:16 offset1:24
	ds_read2_b32 v[32:33], v3 offset0:49 offset1:57
	ds_read2_b32 v[34:35], v3 offset0:82 offset1:90
	ds_read2_b32 v[36:37], v3 offset0:115 offset1:123
	ds_read2_b32 v[38:39], v3 offset0:148 offset1:156
	ds_read2_b32 v[40:41], v3 offset0:181 offset1:189
	ds_read2_b32 v[42:43], v3 offset0:214 offset1:222
	ds_read2_b32 v[44:45], v3 offset0:247 offset1:255
	v_add_u32_e32 v48, 16, v46
	s_waitcnt lgkmcnt(7)
	v_mul_f32_e32 v17, v22, v30
	s_waitcnt lgkmcnt(6)
	v_mul_f32_e32 v26, v23, v32
	v_ashrrev_i32_e32 v49, 31, v48
	v_cvt_pk_bf16_f32 v26, v17, v26
	v_lshlrev_b64 v[48:49], 12, v[48:49]
	v_mul_f32_e32 v17, v22, v31
	v_mul_f32_e32 v22, v23, v33
	s_waitcnt lgkmcnt(5)
	v_mul_f32_e32 v27, v24, v34
	s_waitcnt lgkmcnt(4)
	v_mul_f32_e32 v28, v25, v36
	s_waitcnt lgkmcnt(3)
	v_mul_f32_e32 v29, v18, v38
	v_lshl_add_u64 v[48:49], v[10:11], 0, v[48:49]
	v_mul_f32_e32 v23, v24, v35
	v_mul_f32_e32 v24, v25, v37
	v_mul_f32_e32 v25, v18, v39
	v_cvt_pk_bf16_f32 v18, v17, v22
	v_add_u32_e32 v22, 24, v46
	s_waitcnt lgkmcnt(2)
	v_mul_f32_e32 v30, v19, v40
	s_waitcnt lgkmcnt(1)
	v_mul_f32_e32 v32, v20, v42
	s_waitcnt lgkmcnt(0)
	v_mul_f32_e32 v34, v21, v44
	v_cvt_pk_bf16_f32 v27, v27, v28
	v_cvt_pk_bf16_f32 v28, v29, v30
	v_cvt_pk_bf16_f32 v29, v32, v34
	global_store_dwordx4 v[48:49], v[26:29], off sc0 sc1
	v_mul_f32_e32 v21, v21, v45
	s_nop 0
	v_mul_f32_e32 v26, v19, v41
	v_cvt_pk_bf16_f32 v19, v23, v24
	v_ashrrev_i32_e32 v23, 31, v22
	v_lshlrev_b64 v[22:23], 12, v[22:23]
	v_lshl_add_u64 v[10:11], v[10:11], 0, v[22:23]
	v_mul_f32_e32 v27, v20, v43
	v_cvt_pk_bf16_f32 v20, v25, v26
	v_cvt_pk_bf16_f32 v21, v27, v21
	global_store_dwordx4 v[10:11], v[18:21], off sc0 sc1
	s_waitcnt lgkmcnt(0)
	s_cbranch_scc1 .LBB0_707
	s_mov_b32 s24, s70
